# combination: scan third staging piece unconditional + attention items prefetch the next queue index
# speedup vs baseline: 1.0060x; 1.0060x over previous
.LBB0_923:
	v_cvt_pk_bf16_f32 v122, v118, v119
	v_cvt_pk_bf16_f32 v123, v120, v121
	v_cvt_pk_bf16_f32 v124, v114, v115
	v_cvt_pk_bf16_f32 v125, v116, v117
	v_cvt_pk_bf16_f32 v130, v110, v111
	v_cvt_pk_bf16_f32 v131, v112, v113
	s_nop 0
	v_and_b32_e32 v102, 0xffff0000, v122
	v_lshlrev_b32_e32 v2, 16, v122
	v_sub_f32_e32 v102, v119, v102
	v_sub_f32_e32 v2, v118, v2
	v_cvt_pk_bf16_f32 v126, v2, v102
	v_and_b32_e32 v102, 0xffff0000, v123
	v_lshlrev_b32_e32 v2, 16, v123
	v_sub_f32_e32 v102, v121, v102
	v_sub_f32_e32 v2, v120, v2
	v_cvt_pk_bf16_f32 v127, v2, v102
	v_and_b32_e32 v102, 0xffff0000, v124
	v_lshlrev_b32_e32 v2, 16, v124
	v_sub_f32_e32 v102, v115, v102
	v_sub_f32_e32 v2, v114, v2
	v_cvt_pk_bf16_f32 v128, v2, v102
	v_and_b32_e32 v102, 0xffff0000, v125
	v_lshlrev_b32_e32 v2, 16, v125
	v_sub_f32_e32 v102, v117, v102
	v_sub_f32_e32 v2, v116, v2
	v_cvt_pk_bf16_f32 v129, v2, v102
	v_and_b32_e32 v102, 0xffff0000, v130
	v_lshlrev_b32_e32 v2, 16, v130
	v_sub_f32_e32 v102, v111, v102
	v_sub_f32_e32 v2, v110, v2
	v_cvt_pk_bf16_f32 v146, v2, v102
	v_and_b32_e32 v102, 0xffff0000, v131
	v_lshlrev_b32_e32 v2, 16, v131
	v_sub_f32_e32 v102, v113, v102
	v_sub_f32_e32 v2, v112, v2
	v_cvt_pk_bf16_f32 v147, v2, v102
	s_waitcnt lgkmcnt(14)
	v_mfma_f32_16x16x32_bf16 v[102:105], v[92:95], v[122:125], 0
	v_cvt_pk_bf16_f32 v132, v106, v107
	v_cvt_pk_bf16_f32 v133, v108, v109
	s_waitcnt lgkmcnt(3)
	v_mov_b32_e32 v160, v100
	v_mfma_f32_16x16x32_bf16 v[92:95], v[92:95], v[126:129], v[102:105]
	v_lshlrev_b32_e32 v2, 16, v132
	v_sub_f32_e32 v2, v106, v2
	v_and_b32_e32 v134, 0xffff0000, v132
	v_mfma_f32_16x16x32_bf16 v[92:95], v[88:91], v[130:133], v[92:95]
	v_sub_f32_e32 v134, v107, v134
	v_cvt_pk_bf16_f32 v148, v2, v134
	v_lshlrev_b32_e32 v2, 16, v133
	v_sub_f32_e32 v2, v108, v2
	v_and_b32_e32 v102, 0xffff0000, v133
	v_sub_f32_e32 v102, v109, v102
	v_cvt_pk_bf16_f32 v149, v2, v102
	v_mov_b32_e32 v2, v3
	v_mfma_f32_16x16x32_bf16 v[88:91], v[88:91], v[146:149], v[92:95]
	v_mov_b32_e32 v102, v3
	v_mov_b32_e32 v103, v3
	v_mov_b32_e32 v161, v101
	v_mfma_f32_16x16x32_bf16 v[92:95], v[76:79], v[122:125], 0
	v_mul_f32_e64 v98, v120, v98
	v_mul_f32_e64 v99, v121, v99
	v_pk_mul_f32 v[96:97], v[118:119], v[96:97]
	s_waitcnt lgkmcnt(0)
	v_mfma_f32_16x16x32_bf16 v[154:157], v[0:3], v[100:103], v[88:91]
	s_barrier
	s_nop 1
	ds_read_b128 v[88:91], v204 offset:11008
	ds_read_b128 v[150:153], v204 offset:13056
	v_mfma_f32_16x16x32_bf16 v[102:105], v[76:79], v[126:129], v[92:95]
	ds_read_b128 v[142:145], v205 offset:11008
	s_nop 1
	ds_read_b128 v[92:95], v205 offset:13056
	ds_read_b64 v[76:77], v206 offset:15104
	ds_read_b128 v[138:141], v207 offset:15616
	v_mfma_f32_16x16x32_bf16 v[102:105], v[72:75], v[130:133], v[102:105]
	ds_read_b128 v[130:133], v207 offset:15872
	ds_read_b128 v[122:125], v207 offset:16128
	ds_read_b128 v[134:137], v208 offset:21824
	ds_read_b128 v[126:129], v208 offset:21888
	v_mfma_f32_16x16x32_bf16 v[72:75], v[72:75], v[146:149], v[102:105]
	s_nop 2
	ds_read_b128 v[100:103], v208 offset:21760
	ds_read_b128 v[118:121], v207 offset:16384
	s_nop 2
	v_cvt_pk_bf16_f32 v158, -v72, -v73
	v_cvt_pk_bf16_f32 v159, -v74, -v75
	v_lshlrev_b32_e32 v0, 16, v158
	v_and_b32_e32 v1, 0xffff0000, v158
	v_sub_f32_e64 v0, -v72, v0
	v_sub_f32_e64 v1, -v73, v1
	v_mfma_f32_16x16x32_bf16 v[96:99], v[60:63], v[158:161], v[96:99]
	v_cvt_pk_bf16_f32 v0, v0, v1
	v_lshlrev_b32_e32 v1, 16, v159
	v_and_b32_e32 v2, 0xffff0000, v159
	v_sub_f32_e64 v1, -v74, v1
	v_sub_f32_e64 v2, -v75, v2
	v_cvt_pk_bf16_f32 v1, v1, v2
	v_mov_b32_e32 v2, v3
	s_nop 1
	v_mfma_f32_16x16x32_bf16 v[96:99], v[60:63], v[0:3], v[96:99]
	v_mul_f32_e64 v62, v116, v86
	v_mul_f32_e64 v63, v117, v87
	v_pk_mul_f32 v[60:61], v[114:115], v[84:85]
	ds_read_b64 v[84:85], v209 offset:19712
	ds_read_b128 v[114:117], v208 offset:21952
	v_mfma_f32_16x16x32_bf16 v[60:63], v[56:59], v[158:161], v[60:63]
	v_mfma_f32_16x16x32_bf16 v[146:149], v[56:59], v[0:3], v[60:63]
	v_mul_f32_e64 v58, v112, v70
	v_mul_f32_e64 v59, v113, v71
	v_pk_mul_f32 v[56:57], v[110:111], v[68:69]
	s_nop 3
	v_mfma_f32_16x16x32_bf16 v[56:59], v[52:55], v[158:161], v[56:59]
	s_nop 0
	v_mfma_f32_16x16x32_bf16 v[110:113], v[52:55], v[0:3], v[56:59]
	v_mul_f32_e64 v54, v108, v82
	v_mul_f32_e64 v55, v109, v83
	v_pk_mul_f32 v[52:53], v[106:107], v[80:81]
	s_nop 0
	s_nop 0
	v_mfma_f32_16x16x32_bf16 v[52:55], v[64:67], v[158:161], v[52:55]
	global_store_dword v250, v154, s[24:25] offset:-4096
	v_mfma_f32_16x16x32_bf16 v[106:109], v[64:67], v[0:3], v[52:55]
	global_store_dword v250, v155, s[24:25] offset:-2048
	global_store_dword v250, v156, s[24:25]
	global_store_dword v250, v157, s[24:25] offset:2048
	v_add_u32_e32 v250, 0x8000, v250
	s_waitcnt vmcnt(19)
	ds_write_b128 v181, v[20:23]
	s_waitcnt vmcnt(18)
	ds_write_b128 v188, v[24:27]
	ds_write_b128 v189, v[28:31]
	s_cmpk_gt_u32 s34, 0xf9
	s_cbranch_scc1 .LBB0_929
	global_load_dwordx4 v[20:23], v248, s[100:101] offset:-4096
	s_nop 0
	global_load_dwordx4 v[24:27], v248, s[100:101]
	global_load_dwordx4 v[28:31], v249, s[100:101]

.LBB0_929:
	v_cvt_pk_bf16_f32 v52, v96, v97
	v_cvt_pk_bf16_f32 v53, v98, v99
	v_cvt_pk_bf16_f32 v54, v146, v147
	v_cvt_pk_bf16_f32 v55, v148, v149
	v_cvt_pk_bf16_f32 v60, v110, v111
	v_cvt_pk_bf16_f32 v61, v112, v113
	s_nop 0
	v_lshlrev_b32_e32 v0, 16, v52
	v_and_b32_e32 v1, 0xffff0000, v52
	v_sub_f32_e32 v0, v96, v0
	v_sub_f32_e32 v1, v97, v1
	v_cvt_pk_bf16_f32 v56, v0, v1
	v_lshlrev_b32_e32 v0, 16, v53
	v_and_b32_e32 v1, 0xffff0000, v53
	v_sub_f32_e32 v0, v98, v0
	v_sub_f32_e32 v1, v99, v1
	s_waitcnt lgkmcnt(14)
	v_mfma_f32_16x16x32_bf16 v[66:69], v[150:153], v[52:55], 0
	v_cvt_pk_bf16_f32 v57, v0, v1
	v_lshlrev_b32_e32 v0, 16, v54
	v_and_b32_e32 v1, 0xffff0000, v54
	v_sub_f32_e32 v0, v146, v0
	v_sub_f32_e32 v1, v147, v1
	v_cvt_pk_bf16_f32 v58, v0, v1
	v_lshlrev_b32_e32 v0, 16, v55
	v_and_b32_e32 v1, 0xffff0000, v55
	v_sub_f32_e32 v0, v148, v0
	v_sub_f32_e32 v1, v149, v1
	v_cvt_pk_bf16_f32 v59, v0, v1
	v_lshlrev_b32_e32 v0, 16, v60
	v_mfma_f32_16x16x32_bf16 v[68:71], v[150:153], v[56:59], v[66:69]
	v_and_b32_e32 v1, 0xffff0000, v60
	v_sub_f32_e32 v0, v110, v0
	v_sub_f32_e32 v1, v111, v1
	v_cvt_pk_bf16_f32 v64, v0, v1
	v_lshlrev_b32_e32 v0, 16, v61
	v_and_b32_e32 v1, 0xffff0000, v61
	v_cvt_pk_bf16_f32 v62, v106, v107
	v_cvt_pk_bf16_f32 v63, v108, v109
	v_sub_f32_e32 v0, v112, v0
	v_sub_f32_e32 v1, v113, v1
	s_waitcnt lgkmcnt(12)
	v_mfma_f32_16x16x32_bf16 v[68:71], v[92:95], v[60:63], v[68:71]
	v_cvt_pk_bf16_f32 v65, v0, v1
	v_lshlrev_b32_e32 v0, 16, v62
	v_and_b32_e32 v1, 0xffff0000, v62
	v_mfma_f32_16x16x32_bf16 v[52:55], v[88:91], v[52:55], 0
	v_sub_f32_e32 v0, v106, v0
	v_sub_f32_e32 v1, v107, v1
	v_cvt_pk_bf16_f32 v66, v0, v1
	v_lshlrev_b32_e32 v0, 16, v63
	v_and_b32_e32 v1, 0xffff0000, v63
	v_mov_b32_e32 v78, v3
	v_mov_b32_e32 v79, v3
	v_sub_f32_e32 v0, v108, v0
	v_sub_f32_e32 v1, v109, v1
	v_cvt_pk_bf16_f32 v67, v0, v1
	v_mfma_f32_16x16x32_bf16 v[52:55], v[88:91], v[56:59], v[52:55]
	v_mov_b32_e32 v86, v3
	v_mov_b32_e32 v87, v3
	v_mfma_f32_16x16x32_bf16 v[68:71], v[92:95], v[64:67], v[68:71]
	s_waitcnt lgkmcnt(6)
	v_pk_mul_f32 v[112:113], v[128:129], v[112:113]
	v_pk_mul_f32 v[110:111], v[126:127], v[110:111]
	s_waitcnt lgkmcnt(2)
	v_pk_mul_f32 v[108:109], v[116:117], v[108:109]
	v_mfma_f32_16x16x32_bf16 v[156:159], v[76:79], v[84:87], v[68:71]
	v_mul_f32_e64 v106, v114, v106
	v_mul_f32_e64 v107, v115, v107
	s_waitcnt lgkmcnt(0)
	s_barrier
	v_mfma_f32_16x16x32_bf16 v[68:71], v[142:145], v[60:63], v[52:55]
	ds_read_b128 v[76:79], v204
	ds_read_b128 v[92:95], v204 offset:2048
	ds_read_b128 v[72:75], v205
	ds_read_b128 v[88:91], v205 offset:2048
	ds_read_b64 v[104:105], v206 offset:4096
	ds_read_b128 v[60:63], v207 offset:4608
	ds_read_b128 v[56:59], v207 offset:4864
	ds_read_b128 v[52:55], v207 offset:5120
	v_mfma_f32_16x16x32_bf16 v[64:67], v[142:145], v[64:67], v[68:71]
	v_mov_b32_e32 v144, v84
	v_mov_b32_e32 v145, v85
	s_nop 0
	v_pk_mul_f32 v[70:71], v[102:103], v[98:99]
	v_pk_mul_f32 v[68:69], v[100:101], v[96:97]
	s_nop 2
	v_cvt_pk_bf16_f32 v142, -v64, -v65
	v_cvt_pk_bf16_f32 v143, -v66, -v67
	v_lshlrev_b32_e32 v0, 16, v142
	v_and_b32_e32 v1, 0xffff0000, v142
	v_sub_f32_e64 v0, -v64, v0
	v_sub_f32_e64 v1, -v65, v1
	v_mfma_f32_16x16x32_bf16 v[68:71], v[138:141], v[142:145], v[68:71]
	v_cvt_pk_bf16_f32 v0, v0, v1
	v_lshlrev_b32_e32 v1, 16, v143
	v_and_b32_e32 v2, 0xffff0000, v143
	v_sub_f32_e64 v1, -v66, v1
	v_sub_f32_e64 v2, -v67, v2
	v_pk_mul_f32 v[66:67], v[136:137], v[148:149]
	v_pk_mul_f32 v[64:65], v[134:135], v[146:147]
	v_cvt_pk_bf16_f32 v1, v1, v2
	v_mov_b32_e32 v2, v3
	v_mfma_f32_16x16x32_bf16 v[134:137], v[130:133], v[142:145], v[64:67]
	s_nop 0
	v_mfma_f32_16x16x32_bf16 v[110:113], v[122:125], v[142:145], v[110:113]
	v_mfma_f32_16x16x32_bf16 v[106:109], v[118:121], v[142:145], v[106:109]
	s_nop 0
	v_mfma_f32_16x16x32_bf16 v[138:141], v[138:141], v[0:3], v[68:71]
	ds_read_b128 v[84:87], v208 offset:10816
	s_nop 1
	ds_read_b128 v[68:71], v208 offset:10880
	ds_read_b128 v[96:99], v208 offset:10752
	ds_read_b128 v[64:67], v207 offset:5376
	ds_read_b64 v[100:101], v209 offset:8704
	ds_read_b128 v[80:83], v208 offset:10944
	global_store_dword v250, v156, s[24:25] offset:-4096
	v_mfma_f32_16x16x32_bf16 v[146:149], v[130:133], v[0:3], v[134:137]
	global_store_dword v250, v157, s[24:25] offset:-2048
	global_store_dword v250, v158, s[24:25]
	global_store_dword v250, v159, s[24:25] offset:2048
	v_add_u32_e32 v250, 0x8000, v250
	s_waitcnt vmcnt(17)
	ds_write_b128 v181, v[32:35] offset:11008
	s_waitcnt vmcnt(16)
	ds_write_b128 v188, v[36:39] offset:11008
	v_mfma_f32_16x16x32_bf16 v[152:155], v[122:125], v[0:3], v[110:113]
	v_mfma_f32_16x16x32_bf16 v[158:161], v[118:121], v[0:3], v[106:109]
	ds_write_b128 v189, v[40:43] offset:11008
	s_cmpk_gt_u32 s34, 0xf8
	s_cbranch_scc1 .LBB0_935
	global_load_dwordx4 v[32:35], v248, s[100:101] offset:-4096
	s_nop 0
	global_load_dwordx4 v[36:39], v248, s[100:101]
	global_load_dwordx4 v[40:43], v249, s[100:101]

.LBB0_935:
	v_cvt_pk_bf16_f32 v108, v138, v139
	v_cvt_pk_bf16_f32 v109, v140, v141
	v_cvt_pk_bf16_f32 v110, v146, v147
	v_cvt_pk_bf16_f32 v111, v148, v149
	v_cvt_pk_bf16_f32 v122, v152, v153
	v_cvt_pk_bf16_f32 v123, v154, v155
	s_nop 0
	v_lshlrev_b32_e32 v0, 16, v108
	v_and_b32_e32 v1, 0xffff0000, v108
	v_sub_f32_e32 v0, v138, v0
	v_sub_f32_e32 v1, v139, v1
	v_cvt_pk_bf16_f32 v112, v0, v1
	v_lshlrev_b32_e32 v0, 16, v109
	v_and_b32_e32 v1, 0xffff0000, v109
	v_sub_f32_e32 v0, v140, v0
	v_sub_f32_e32 v1, v141, v1
	s_waitcnt lgkmcnt(14)
	v_mfma_f32_16x16x32_bf16 v[116:119], v[92:95], v[108:111], 0
	v_cvt_pk_bf16_f32 v113, v0, v1
	v_lshlrev_b32_e32 v0, 16, v110
	v_and_b32_e32 v1, 0xffff0000, v110
	v_sub_f32_e32 v0, v146, v0
	v_sub_f32_e32 v1, v147, v1
	v_cvt_pk_bf16_f32 v114, v0, v1
	v_lshlrev_b32_e32 v0, 16, v111
	v_and_b32_e32 v1, 0xffff0000, v111
	v_sub_f32_e32 v0, v148, v0
	v_sub_f32_e32 v1, v149, v1
	v_cvt_pk_bf16_f32 v115, v0, v1
	v_lshlrev_b32_e32 v0, 16, v122
	v_mfma_f32_16x16x32_bf16 v[116:119], v[92:95], v[112:115], v[116:119]
	v_and_b32_e32 v1, 0xffff0000, v122
	v_sub_f32_e32 v0, v152, v0
	v_sub_f32_e32 v1, v153, v1
	v_cvt_pk_bf16_f32 v126, v0, v1
	v_lshlrev_b32_e32 v0, 16, v123
	v_and_b32_e32 v1, 0xffff0000, v123
	v_cvt_pk_bf16_f32 v124, v158, v159
	v_cvt_pk_bf16_f32 v125, v160, v161
	v_sub_f32_e32 v0, v154, v0
	v_sub_f32_e32 v1, v155, v1
	s_waitcnt lgkmcnt(12)
	v_mfma_f32_16x16x32_bf16 v[116:119], v[88:91], v[122:125], v[116:119]
	v_cvt_pk_bf16_f32 v127, v0, v1
	v_lshlrev_b32_e32 v0, 16, v124
	v_and_b32_e32 v1, 0xffff0000, v124
	v_sub_f32_e32 v0, v158, v0
	v_sub_f32_e32 v1, v159, v1
	v_cvt_pk_bf16_f32 v128, v0, v1
	v_lshlrev_b32_e32 v0, 16, v125
	v_and_b32_e32 v1, 0xffff0000, v125
	v_mov_b32_e32 v106, v3
	v_mov_b32_e32 v107, v3
	v_sub_f32_e32 v0, v160, v0
	v_sub_f32_e32 v1, v161, v1
	v_cvt_pk_bf16_f32 v129, v0, v1
	v_mov_b32_e32 v102, v3
	v_mfma_f32_16x16x32_bf16 v[116:119], v[88:91], v[126:129], v[116:119]
	v_mov_b32_e32 v103, v3
	s_waitcnt lgkmcnt(3)
	v_mov_b32_e32 v216, v100
	v_mov_b32_e32 v217, v101
	v_mfma_f32_16x16x32_bf16 v[210:213], v[104:107], v[100:103], v[116:119]
	v_mul_f32_e64 v154, v70, v154
	v_mul_f32_e64 v155, v71, v155
	v_pk_mul_f32 v[152:153], v[68:69], v[152:153]
	s_waitcnt lgkmcnt(2)
	v_pk_mul_f32 v[160:161], v[82:83], v[160:161]
	v_mfma_f32_16x16x32_bf16 v[106:109], v[76:79], v[108:111], 0
	v_mul_f32_e64 v158, v80, v158
	v_mul_f32_e64 v159, v81, v159
	s_waitcnt lgkmcnt(0)
	s_barrier
	v_mfma_f32_16x16x32_bf16 v[106:109], v[76:79], v[112:115], v[106:109]
	ds_read_b128 v[118:121], v204 offset:11008
	ds_read_b128 v[170:173], v204 offset:13056
	ds_read_b128 v[134:137], v205 offset:11008
	ds_read_b128 v[162:165], v205 offset:13056
	v_mfma_f32_16x16x32_bf16 v[122:125], v[72:75], v[122:125], v[106:109]
	ds_read_b64 v[150:151], v206 offset:15104
	ds_read_b128 v[114:117], v207 offset:15616
	ds_read_b128 v[110:113], v207 offset:15872
	ds_read_b128 v[106:109], v207 offset:16128
	v_mfma_f32_16x16x32_bf16 v[122:125], v[72:75], v[126:129], v[122:125]
	v_mul_f32_e64 v128, v98, v140
	v_mul_f32_e64 v129, v99, v141
	v_pk_mul_f32 v[126:127], v[96:97], v[138:139]
	ds_read_b128 v[138:141], v208 offset:21824
	ds_read_b128 v[130:133], v208 offset:21888
	s_nop 1
	s_nop 0
	v_cvt_pk_bf16_f32 v214, -v122, -v123
	v_cvt_pk_bf16_f32 v215, -v124, -v125
	v_lshlrev_b32_e32 v0, 16, v214
	v_and_b32_e32 v1, 0xffff0000, v214
	v_sub_f32_e64 v0, -v122, v0
	v_sub_f32_e64 v1, -v123, v1
	v_mfma_f32_16x16x32_bf16 v[126:129], v[60:63], v[214:217], v[126:129]
	v_cvt_pk_bf16_f32 v0, v0, v1
	v_lshlrev_b32_e32 v1, 16, v215
	v_and_b32_e32 v2, 0xffff0000, v215
	v_sub_f32_e64 v1, -v124, v1
	v_sub_f32_e64 v2, -v125, v2
	v_pk_mul_f32 v[124:125], v[86:87], v[148:149]
	v_pk_mul_f32 v[122:123], v[84:85], v[146:147]
	v_cvt_pk_bf16_f32 v1, v1, v2
	v_mov_b32_e32 v2, v3
	v_mfma_f32_16x16x32_bf16 v[152:155], v[52:55], v[214:217], v[152:155]
	s_cmpk_lt_u32 s34, 0xfc
	v_mfma_f32_16x16x32_bf16 v[146:149], v[56:59], v[214:217], v[122:125]
	s_cselect_b64 s[12:13], -1, 0
	s_cmpk_gt_u32 s34, 0xfb
	v_mfma_f32_16x16x32_bf16 v[158:161], v[64:67], v[214:217], v[158:161]
	s_cselect_b64 s[40:41], -1, 0
	s_and_b64 vcc, exec, s[40:41]
	v_mfma_f32_16x16x32_bf16 v[142:145], v[60:63], v[0:3], v[126:129]
	ds_read_b128 v[166:169], v208 offset:21760
	ds_read_b128 v[122:125], v207 offset:16384
	ds_read_b64 v[174:175], v209 offset:19712
	ds_read_b128 v[126:129], v208 offset:21952
	global_store_dword v250, v210, s[24:25] offset:-4096
	global_store_dword v250, v211, s[24:25] offset:-2048
	global_store_dword v250, v212, s[24:25]
	global_store_dword v250, v213, s[24:25] offset:2048
	v_add_u32_e32 v250, 0x8000, v250
	v_mfma_f32_16x16x32_bf16 v[146:149], v[56:59], v[0:3], v[146:149]
	v_mfma_f32_16x16x32_bf16 v[154:157], v[52:55], v[0:3], v[152:155]
	v_mfma_f32_16x16x32_bf16 v[158:161], v[64:67], v[0:3], v[158:161]
	s_cbranch_vccnz .LBB0_939
	s_waitcnt vmcnt(23)
	ds_write_b128 v181, v[44:47]
	s_waitcnt vmcnt(22)
	ds_write_b128 v188, v[48:51]
	ds_write_b128 v189, v[4:7]
